# v42 with all remaining per-segment s_setprio flips deleted from the GEMM K-loops (no priority changes at all)
# baseline (speedup 1.0000x reference)
.LBB0_306:
	s_ashr_i32 s51, s50, 31
	s_lshl_b64 s[12:13], s[50:51], 19
	s_add_u32 s52, s8, s12
	s_addc_u32 s53, s9, s13
	s_and_b64 s[12:13], s[38:39], exec
	s_cselect_b32 s73, s53, s57
	s_cselect_b32 s74, s52, s56
	s_ashr_i32 s49, s48, 31
	s_lshl_b64 s[12:13], s[48:49], 19
	s_add_u32 s54, s2, s12
	s_addc_u32 s55, s16, s13
	s_and_b64 s[12:13], s[38:39], exec
	s_cselect_b32 s75, s55, s59
	s_cselect_b32 s76, s54, s58
	s_lshl_b64 s[12:13], s[50:51], 11
	v_lshl_add_u64 v[50:51], v[166:167], 0, s[12:13]
	s_lshl_b32 s12, s71, 12
	s_and_b32 s51, s12, 0x1000
	s_lshl_b64 s[12:13], s[48:49], 10
	s_add_u32 s56, s56, 0x40080
	s_addc_u32 s57, s57, 0
	v_lshl_add_u64 v[52:53], v[168:169], 0, s[12:13]
	s_add_u32 s12, s58, 0x100
	s_addc_u32 s13, s59, 0
	s_add_i32 s51, s23, s51
	s_mov_b32 s49, -2
	s_add_i32 s77, s51, 0x800
	s_mov_b64 s[58:59], 0
	s_add_u32 s60, s56, 0xfffc0080
	s_addc_u32 s61, s57, -1
	s_and_b64 s[58:59], s[58:59], exec
	s_cselect_b32 s61, s73, s61
	s_cselect_b32 s60, s74, s60
	s_cselect_b32 s59, s75, s13
	s_cselect_b32 s58, s76, s12
	s_add_i32 s80, 0, 0x10000
	s_add_i32 s82, 0, 0x14000
	v_add_u32_e32 v146, s80, v165
	v_add_u32_e32 v182, s82, v165
	ds_read_b128 v[54:57], v146
	ds_read_b128 v[66:69], v146 offset:1024
	ds_read_b128 v[70:73], v146 offset:2048
	ds_read_b128 v[146:149], v146 offset:3072
	ds_read_b128 v[150:153], v182
	ds_read_b128 v[174:177], v182 offset:1024
	ds_read_b128 v[178:181], v182 offset:2048
	ds_read_b128 v[182:185], v182 offset:3072
	v_lshl_add_u64 v[224:225], s[56:57], 0, v[170:171]
	s_add_i32 m0, s64, 0xc000
	ds_read_b128 v[190:193], v188
	ds_read_b128 v[194:197], v188 offset:1024
	ds_read_b128 v[198:201], v188 offset:2048
	ds_read_b128 v[202:205], v188 offset:3072
	ds_read_b128 v[208:211], v188 offset:4096
	ds_read_b128 v[212:215], v188 offset:5120
	ds_read_b128 v[216:219], v188 offset:6144
	ds_read_b128 v[220:223], v188 offset:7168
	global_load_lds_dwordx4 v[224:225], off
	v_lshl_add_u64 v[224:225], s[56:57], 0, v[172:173]
	s_add_i32 m0, s64, 0xe000
	s_nop 0
	global_load_lds_dwordx4 v[224:225], off
	s_waitcnt vmcnt(8)
	s_waitcnt lgkmcnt(0)
	s_barrier
	s_waitcnt lgkmcnt(0)
	v_mfma_f32_16x16x32_bf16 v[142:145], v[54:57], v[190:193], 0
	v_mfma_f32_16x16x32_bf16 v[134:137], v[70:73], v[190:193], 0
	v_mfma_f32_16x16x32_bf16 v[126:129], v[54:57], v[198:201], 0
	v_mfma_f32_16x16x32_bf16 v[118:121], v[70:73], v[198:201], 0
	v_mfma_f32_16x16x32_bf16 v[110:113], v[54:57], v[208:211], 0
	v_mfma_f32_16x16x32_bf16 v[102:105], v[70:73], v[208:211], 0
	v_mfma_f32_16x16x32_bf16 v[94:97], v[54:57], v[216:219], 0
	v_mfma_f32_16x16x32_bf16 v[86:89], v[70:73], v[216:219], 0
	v_mfma_f32_16x16x32_bf16 v[142:145], v[66:69], v[194:197], v[142:145]
	v_mfma_f32_16x16x32_bf16 v[134:137], v[146:149], v[194:197], v[134:137]
	v_mfma_f32_16x16x32_bf16 v[126:129], v[66:69], v[202:205], v[126:129]
	v_mfma_f32_16x16x32_bf16 v[118:121], v[146:149], v[202:205], v[118:121]
	v_mfma_f32_16x16x32_bf16 v[110:113], v[66:69], v[212:215], v[110:113]
	v_mfma_f32_16x16x32_bf16 v[102:105], v[146:149], v[212:215], v[102:105]
	v_mfma_f32_16x16x32_bf16 v[94:97], v[66:69], v[220:223], v[94:97]
	v_mfma_f32_16x16x32_bf16 v[86:89], v[146:149], v[220:223], v[86:89]
	v_mfma_f32_16x16x32_bf16 v[138:141], v[150:153], v[190:193], 0
	v_mfma_f32_16x16x32_bf16 v[130:133], v[178:181], v[190:193], 0
	v_mfma_f32_16x16x32_bf16 v[122:125], v[150:153], v[198:201], 0
	v_mfma_f32_16x16x32_bf16 v[114:117], v[178:181], v[198:201], 0
	v_mfma_f32_16x16x32_bf16 v[106:109], v[150:153], v[208:211], 0
	v_mfma_f32_16x16x32_bf16 v[98:101], v[178:181], v[208:211], 0
	v_mfma_f32_16x16x32_bf16 v[90:93], v[150:153], v[216:219], 0
	v_mfma_f32_16x16x32_bf16 v[82:85], v[178:181], v[216:219], 0
	v_mfma_f32_16x16x32_bf16 v[138:141], v[174:177], v[194:197], v[138:141]
	v_mfma_f32_16x16x32_bf16 v[130:133], v[182:185], v[194:197], v[130:133]
	v_mfma_f32_16x16x32_bf16 v[122:125], v[174:177], v[202:205], v[122:125]
	v_mfma_f32_16x16x32_bf16 v[114:117], v[182:185], v[202:205], v[114:117]
	v_mfma_f32_16x16x32_bf16 v[106:109], v[174:177], v[212:215], v[106:109]
	v_mfma_f32_16x16x32_bf16 v[98:101], v[182:185], v[212:215], v[98:101]
	v_mfma_f32_16x16x32_bf16 v[90:93], v[174:177], v[220:223], v[90:93]
	v_mfma_f32_16x16x32_bf16 v[82:85], v[182:185], v[220:223], v[82:85]
	s_barrier
	s_add_i32 s80, s80, s22
	v_lshl_add_u64 v[224:225], s[58:59], 0, v[158:159]
	s_mov_b32 m0, s80
	ds_read_b128 v[190:193], v188 offset:16384
	ds_read_b128 v[194:197], v188 offset:17408
	ds_read_b128 v[198:201], v188 offset:18432
	ds_read_b128 v[202:205], v188 offset:19456
	ds_read_b128 v[208:211], v188 offset:20480
	ds_read_b128 v[212:215], v188 offset:21504
	ds_read_b128 v[216:219], v188 offset:22528
	ds_read_b128 v[220:223], v188 offset:23552
	global_load_lds_dwordx4 v[224:225], off
	s_add_i32 m0, s80, 0x2000
	s_add_u32 s80, s58, 0x40000
	v_lshl_add_u64 v[226:227], s[58:59], 0, v[154:155]
	s_addc_u32 s81, s59, 0
	s_add_i32 s82, s82, s22
	global_load_lds_dwordx4 v[226:227], off
	v_lshl_add_u64 v[228:229], s[80:81], 0, v[158:159]
	s_mov_b32 m0, s82
	v_lshl_add_u64 v[230:231], s[60:61], 0, v[156:157]
	global_load_lds_dwordx4 v[228:229], off
	v_lshl_add_u64 v[228:229], s[80:81], 0, v[154:155]
	s_add_i32 m0, s82, 0x2000
	s_nop 0
	global_load_lds_dwordx4 v[228:229], off
	v_lshl_add_u64 v[228:229], s[60:61], 0, v[160:161]
	s_mov_b32 m0, s64
	s_nop 0
	global_load_lds_dwordx4 v[228:229], off
	s_mov_b32 m0, s65
	s_nop 0
	global_load_lds_dwordx4 v[230:231], off
	s_waitcnt vmcnt(8)
	s_waitcnt lgkmcnt(0)
	s_barrier
	s_waitcnt lgkmcnt(0)
	v_mfma_f32_16x16x32_bf16 v[78:81], v[54:57], v[190:193], 0
	v_mfma_f32_16x16x32_bf16 v[62:65], v[70:73], v[190:193], 0
	v_mfma_f32_16x16x32_bf16 v[46:49], v[54:57], v[198:201], 0
	v_mfma_f32_16x16x32_bf16 v[38:41], v[70:73], v[198:201], 0
	v_mfma_f32_16x16x32_bf16 v[30:33], v[54:57], v[208:211], 0
	v_mfma_f32_16x16x32_bf16 v[22:25], v[70:73], v[208:211], 0
	v_mfma_f32_16x16x32_bf16 v[14:17], v[54:57], v[216:219], 0
	v_mfma_f32_16x16x32_bf16 v[6:9], v[70:73], v[216:219], 0
	v_mfma_f32_16x16x32_bf16 v[78:81], v[66:69], v[194:197], v[78:81]
	v_mfma_f32_16x16x32_bf16 v[62:65], v[146:149], v[194:197], v[62:65]
	v_mfma_f32_16x16x32_bf16 v[46:49], v[66:69], v[202:205], v[46:49]
	v_mfma_f32_16x16x32_bf16 v[38:41], v[146:149], v[202:205], v[38:41]
	v_mfma_f32_16x16x32_bf16 v[30:33], v[66:69], v[212:215], v[30:33]
	v_mfma_f32_16x16x32_bf16 v[22:25], v[146:149], v[212:215], v[22:25]
	v_mfma_f32_16x16x32_bf16 v[14:17], v[66:69], v[220:223], v[14:17]
	v_mfma_f32_16x16x32_bf16 v[6:9], v[146:149], v[220:223], v[6:9]
	v_mfma_f32_16x16x32_bf16 v[58:61], v[178:181], v[190:193], 0
	v_mfma_f32_16x16x32_bf16 v[42:45], v[150:153], v[198:201], 0
	v_mfma_f32_16x16x32_bf16 v[34:37], v[178:181], v[198:201], 0
	v_mfma_f32_16x16x32_bf16 v[26:29], v[150:153], v[208:211], 0
	v_mfma_f32_16x16x32_bf16 v[18:21], v[178:181], v[208:211], 0
	v_mfma_f32_16x16x32_bf16 v[10:13], v[150:153], v[216:219], 0
	v_mfma_f32_16x16x32_bf16 v[2:5], v[178:181], v[216:219], 0
	v_mfma_f32_16x16x32_bf16 v[54:57], v[150:153], v[190:193], 0
	v_mfma_f32_16x16x32_bf16 v[58:61], v[182:185], v[194:197], v[58:61]
	v_mfma_f32_16x16x32_bf16 v[42:45], v[174:177], v[202:205], v[42:45]
	v_mfma_f32_16x16x32_bf16 v[34:37], v[182:185], v[202:205], v[34:37]
	v_mfma_f32_16x16x32_bf16 v[26:29], v[174:177], v[212:215], v[26:29]
	v_mfma_f32_16x16x32_bf16 v[18:21], v[182:185], v[212:215], v[18:21]
	v_mfma_f32_16x16x32_bf16 v[10:13], v[174:177], v[220:223], v[10:13]
	v_mfma_f32_16x16x32_bf16 v[2:5], v[182:185], v[220:223], v[2:5]
	v_mfma_f32_16x16x32_bf16 v[54:57], v[174:177], v[194:197], v[54:57]
	s_barrier
	s_branch .Lpeel_mid_sw
.LBB0_307:
	s_add_u32 s60, s56, 0xfffc0080
	s_addc_u32 s61, s57, -1
	s_and_b64 s[58:59], s[58:59], exec
	s_cselect_b32 s61, s73, s61
	s_cselect_b32 s60, s74, s60
	s_cselect_b32 s59, s75, s13
	s_cselect_b32 s58, s76, s12
	s_add_i32 s80, 0, 0x10000
	s_add_i32 s82, 0, 0x14000
	v_add_u32_e32 v146, s80, v165
	v_add_u32_e32 v182, s82, v165
	ds_read_b128 v[54:57], v146
	ds_read_b128 v[66:69], v146 offset:1024
	ds_read_b128 v[70:73], v146 offset:2048
	ds_read_b128 v[146:149], v146 offset:3072
	ds_read_b128 v[150:153], v182
	ds_read_b128 v[174:177], v182 offset:1024
	ds_read_b128 v[178:181], v182 offset:2048
	ds_read_b128 v[182:185], v182 offset:3072
	v_lshl_add_u64 v[224:225], s[56:57], 0, v[170:171]
	s_add_i32 m0, s64, 0xc000
	ds_read_b128 v[190:193], v188
	ds_read_b128 v[194:197], v188 offset:1024
	ds_read_b128 v[198:201], v188 offset:2048
	ds_read_b128 v[202:205], v188 offset:3072
	ds_read_b128 v[208:211], v188 offset:4096
	ds_read_b128 v[212:215], v188 offset:5120
	ds_read_b128 v[216:219], v188 offset:6144
	ds_read_b128 v[220:223], v188 offset:7168
	global_load_lds_dwordx4 v[224:225], off
	v_lshl_add_u64 v[224:225], s[56:57], 0, v[172:173]
	s_add_i32 m0, s64, 0xe000
	s_nop 0
	global_load_lds_dwordx4 v[224:225], off
	s_waitcnt vmcnt(8)
	s_waitcnt lgkmcnt(0)
	s_barrier
	s_waitcnt lgkmcnt(0)
	v_mfma_f32_16x16x32_bf16 v[142:145], v[54:57], v[190:193], v[142:145]
	v_mfma_f32_16x16x32_bf16 v[134:137], v[70:73], v[190:193], v[134:137]
	v_mfma_f32_16x16x32_bf16 v[126:129], v[54:57], v[198:201], v[126:129]
	v_mfma_f32_16x16x32_bf16 v[118:121], v[70:73], v[198:201], v[118:121]
	v_mfma_f32_16x16x32_bf16 v[110:113], v[54:57], v[208:211], v[110:113]
	v_mfma_f32_16x16x32_bf16 v[102:105], v[70:73], v[208:211], v[102:105]
	v_mfma_f32_16x16x32_bf16 v[94:97], v[54:57], v[216:219], v[94:97]
	v_mfma_f32_16x16x32_bf16 v[86:89], v[70:73], v[216:219], v[86:89]
	v_mfma_f32_16x16x32_bf16 v[142:145], v[66:69], v[194:197], v[142:145]
	v_mfma_f32_16x16x32_bf16 v[134:137], v[146:149], v[194:197], v[134:137]
	v_mfma_f32_16x16x32_bf16 v[126:129], v[66:69], v[202:205], v[126:129]
	v_mfma_f32_16x16x32_bf16 v[118:121], v[146:149], v[202:205], v[118:121]
	v_mfma_f32_16x16x32_bf16 v[110:113], v[66:69], v[212:215], v[110:113]
	v_mfma_f32_16x16x32_bf16 v[102:105], v[146:149], v[212:215], v[102:105]
	v_mfma_f32_16x16x32_bf16 v[94:97], v[66:69], v[220:223], v[94:97]
	v_mfma_f32_16x16x32_bf16 v[86:89], v[146:149], v[220:223], v[86:89]
	v_mfma_f32_16x16x32_bf16 v[138:141], v[150:153], v[190:193], v[138:141]
	v_mfma_f32_16x16x32_bf16 v[130:133], v[178:181], v[190:193], v[130:133]
	v_mfma_f32_16x16x32_bf16 v[122:125], v[150:153], v[198:201], v[122:125]
	v_mfma_f32_16x16x32_bf16 v[114:117], v[178:181], v[198:201], v[114:117]
	v_mfma_f32_16x16x32_bf16 v[106:109], v[150:153], v[208:211], v[106:109]
	v_mfma_f32_16x16x32_bf16 v[98:101], v[178:181], v[208:211], v[98:101]
	v_mfma_f32_16x16x32_bf16 v[90:93], v[150:153], v[216:219], v[90:93]
	v_mfma_f32_16x16x32_bf16 v[82:85], v[178:181], v[216:219], v[82:85]
	v_mfma_f32_16x16x32_bf16 v[138:141], v[174:177], v[194:197], v[138:141]
	v_mfma_f32_16x16x32_bf16 v[130:133], v[182:185], v[194:197], v[130:133]
	v_mfma_f32_16x16x32_bf16 v[122:125], v[174:177], v[202:205], v[122:125]
	v_mfma_f32_16x16x32_bf16 v[114:117], v[182:185], v[202:205], v[114:117]
	v_mfma_f32_16x16x32_bf16 v[106:109], v[174:177], v[212:215], v[106:109]
	v_mfma_f32_16x16x32_bf16 v[98:101], v[182:185], v[212:215], v[98:101]
	v_mfma_f32_16x16x32_bf16 v[90:93], v[174:177], v[220:223], v[90:93]
	v_mfma_f32_16x16x32_bf16 v[82:85], v[182:185], v[220:223], v[82:85]
	s_barrier
	s_add_i32 s80, s80, s22
	v_lshl_add_u64 v[224:225], s[58:59], 0, v[158:159]
	s_mov_b32 m0, s80
	ds_read_b128 v[190:193], v188 offset:16384
	ds_read_b128 v[194:197], v188 offset:17408
	ds_read_b128 v[198:201], v188 offset:18432
	ds_read_b128 v[202:205], v188 offset:19456
	ds_read_b128 v[208:211], v188 offset:20480
	ds_read_b128 v[212:215], v188 offset:21504
	ds_read_b128 v[216:219], v188 offset:22528
	ds_read_b128 v[220:223], v188 offset:23552
	global_load_lds_dwordx4 v[224:225], off
	s_add_i32 m0, s80, 0x2000
	s_add_u32 s80, s58, 0x40000
	v_lshl_add_u64 v[226:227], s[58:59], 0, v[154:155]
	s_addc_u32 s81, s59, 0
	s_add_i32 s82, s82, s22
	global_load_lds_dwordx4 v[226:227], off
	v_lshl_add_u64 v[228:229], s[80:81], 0, v[158:159]
	s_mov_b32 m0, s82
	v_lshl_add_u64 v[230:231], s[60:61], 0, v[156:157]
	global_load_lds_dwordx4 v[228:229], off
	v_lshl_add_u64 v[228:229], s[80:81], 0, v[154:155]
	s_add_i32 m0, s82, 0x2000
	s_nop 0
	global_load_lds_dwordx4 v[228:229], off
	v_lshl_add_u64 v[228:229], s[60:61], 0, v[160:161]
	s_mov_b32 m0, s64
	s_nop 0
	global_load_lds_dwordx4 v[228:229], off
	s_mov_b32 m0, s65
	s_nop 0
	global_load_lds_dwordx4 v[230:231], off
	s_waitcnt vmcnt(8)
	s_waitcnt lgkmcnt(0)
	s_barrier
	s_waitcnt lgkmcnt(0)
	v_mfma_f32_16x16x32_bf16 v[78:81], v[54:57], v[190:193], v[78:81]
	v_mfma_f32_16x16x32_bf16 v[62:65], v[70:73], v[190:193], v[62:65]
	v_mfma_f32_16x16x32_bf16 v[46:49], v[54:57], v[198:201], v[46:49]
	v_mfma_f32_16x16x32_bf16 v[38:41], v[70:73], v[198:201], v[38:41]
	v_mfma_f32_16x16x32_bf16 v[30:33], v[54:57], v[208:211], v[30:33]
	v_mfma_f32_16x16x32_bf16 v[22:25], v[70:73], v[208:211], v[22:25]
	v_mfma_f32_16x16x32_bf16 v[14:17], v[54:57], v[216:219], v[14:17]
	v_mfma_f32_16x16x32_bf16 v[6:9], v[70:73], v[216:219], v[6:9]
	v_mfma_f32_16x16x32_bf16 v[78:81], v[66:69], v[194:197], v[78:81]
	v_mfma_f32_16x16x32_bf16 v[62:65], v[146:149], v[194:197], v[62:65]
	v_mfma_f32_16x16x32_bf16 v[46:49], v[66:69], v[202:205], v[46:49]
	v_mfma_f32_16x16x32_bf16 v[38:41], v[146:149], v[202:205], v[38:41]
	v_mfma_f32_16x16x32_bf16 v[30:33], v[66:69], v[212:215], v[30:33]
	v_mfma_f32_16x16x32_bf16 v[22:25], v[146:149], v[212:215], v[22:25]
	v_mfma_f32_16x16x32_bf16 v[14:17], v[66:69], v[220:223], v[14:17]
	v_mfma_f32_16x16x32_bf16 v[6:9], v[146:149], v[220:223], v[6:9]
	v_mfma_f32_16x16x32_bf16 v[58:61], v[178:181], v[190:193], v[58:61]
	v_mfma_f32_16x16x32_bf16 v[42:45], v[150:153], v[198:201], v[42:45]
	v_mfma_f32_16x16x32_bf16 v[34:37], v[178:181], v[198:201], v[34:37]
	v_mfma_f32_16x16x32_bf16 v[26:29], v[150:153], v[208:211], v[26:29]
	v_mfma_f32_16x16x32_bf16 v[18:21], v[178:181], v[208:211], v[18:21]
	v_mfma_f32_16x16x32_bf16 v[10:13], v[150:153], v[216:219], v[10:13]
	v_mfma_f32_16x16x32_bf16 v[2:5], v[178:181], v[216:219], v[2:5]
	v_mfma_f32_16x16x32_bf16 v[54:57], v[150:153], v[190:193], v[74:77]
	v_mfma_f32_16x16x32_bf16 v[58:61], v[182:185], v[194:197], v[58:61]
	v_mfma_f32_16x16x32_bf16 v[42:45], v[174:177], v[202:205], v[42:45]
	v_mfma_f32_16x16x32_bf16 v[34:37], v[182:185], v[202:205], v[34:37]
	v_mfma_f32_16x16x32_bf16 v[26:29], v[174:177], v[212:215], v[26:29]
	v_mfma_f32_16x16x32_bf16 v[18:21], v[182:185], v[212:215], v[18:21]
	v_mfma_f32_16x16x32_bf16 v[10:13], v[174:177], v[220:223], v[10:13]
	v_mfma_f32_16x16x32_bf16 v[2:5], v[182:185], v[220:223], v[2:5]
	v_mfma_f32_16x16x32_bf16 v[54:57], v[174:177], v[194:197], v[54:57]
	s_barrier
.Lpeel_mid_sw:
	s_add_i32 s80, 0, 0x18000
	s_add_i32 s81, 0, 0x1c000
	v_add_u32_e32 v146, s80, v165
	v_add_u32_e32 v182, s81, v165
	ds_read_b128 v[66:69], v146
	ds_read_b128 v[70:73], v146 offset:1024
	ds_read_b128 v[74:77], v146 offset:2048
	ds_read_b128 v[146:149], v146 offset:3072
	ds_read_b128 v[150:153], v182
	ds_read_b128 v[174:177], v182 offset:1024
	ds_read_b128 v[178:181], v182 offset:2048
	ds_read_b128 v[182:185], v182 offset:3072
	s_add_u32 s60, s60, 0x40000
	s_addc_u32 s61, s61, 0
	s_mov_b32 m0, s66
	v_lshl_add_u64 v[232:233], s[60:61], 0, v[160:161]
	ds_read_b128 v[190:193], v188 offset:32768
	ds_read_b128 v[194:197], v188 offset:33792
	ds_read_b128 v[198:201], v188 offset:34816
	ds_read_b128 v[202:205], v188 offset:35840
	ds_read_b128 v[208:211], v188 offset:36864
	ds_read_b128 v[212:215], v188 offset:37888
	ds_read_b128 v[216:219], v188 offset:38912
	ds_read_b128 v[220:223], v188 offset:39936
	global_load_lds_dwordx4 v[232:233], off
	v_lshl_add_u64 v[232:233], s[60:61], 0, v[156:157]
	s_mov_b32 m0, s67
	s_nop 0
	global_load_lds_dwordx4 v[232:233], off
	s_waitcnt vmcnt(8)
	s_waitcnt lgkmcnt(0)
	s_barrier
	s_waitcnt lgkmcnt(0)
	v_mfma_f32_16x16x32_bf16 v[142:145], v[66:69], v[190:193], v[142:145]
	v_mfma_f32_16x16x32_bf16 v[134:137], v[74:77], v[190:193], v[134:137]
	v_mfma_f32_16x16x32_bf16 v[126:129], v[66:69], v[198:201], v[126:129]
	v_mfma_f32_16x16x32_bf16 v[118:121], v[74:77], v[198:201], v[118:121]
	v_mfma_f32_16x16x32_bf16 v[110:113], v[66:69], v[208:211], v[110:113]
	v_mfma_f32_16x16x32_bf16 v[102:105], v[74:77], v[208:211], v[102:105]
	v_mfma_f32_16x16x32_bf16 v[94:97], v[66:69], v[216:219], v[94:97]
	v_mfma_f32_16x16x32_bf16 v[86:89], v[74:77], v[216:219], v[86:89]
	v_mfma_f32_16x16x32_bf16 v[142:145], v[70:73], v[194:197], v[142:145]
	v_mfma_f32_16x16x32_bf16 v[134:137], v[146:149], v[194:197], v[134:137]
	v_mfma_f32_16x16x32_bf16 v[126:129], v[70:73], v[202:205], v[126:129]
	v_mfma_f32_16x16x32_bf16 v[118:121], v[146:149], v[202:205], v[118:121]
	v_mfma_f32_16x16x32_bf16 v[110:113], v[70:73], v[212:215], v[110:113]
	v_mfma_f32_16x16x32_bf16 v[102:105], v[146:149], v[212:215], v[102:105]
	v_mfma_f32_16x16x32_bf16 v[94:97], v[70:73], v[220:223], v[94:97]
	v_mfma_f32_16x16x32_bf16 v[86:89], v[146:149], v[220:223], v[86:89]
	v_mfma_f32_16x16x32_bf16 v[138:141], v[150:153], v[190:193], v[138:141]
	v_mfma_f32_16x16x32_bf16 v[130:133], v[178:181], v[190:193], v[130:133]
	v_mfma_f32_16x16x32_bf16 v[122:125], v[150:153], v[198:201], v[122:125]
	v_mfma_f32_16x16x32_bf16 v[114:117], v[178:181], v[198:201], v[114:117]
	v_mfma_f32_16x16x32_bf16 v[106:109], v[150:153], v[208:211], v[106:109]
	v_mfma_f32_16x16x32_bf16 v[98:101], v[178:181], v[208:211], v[98:101]
	v_mfma_f32_16x16x32_bf16 v[90:93], v[150:153], v[216:219], v[90:93]
	v_mfma_f32_16x16x32_bf16 v[82:85], v[178:181], v[216:219], v[82:85]
	v_mfma_f32_16x16x32_bf16 v[138:141], v[174:177], v[194:197], v[138:141]
	v_mfma_f32_16x16x32_bf16 v[130:133], v[182:185], v[194:197], v[130:133]
	v_mfma_f32_16x16x32_bf16 v[122:125], v[174:177], v[202:205], v[122:125]
	v_mfma_f32_16x16x32_bf16 v[114:117], v[182:185], v[202:205], v[114:117]
	v_mfma_f32_16x16x32_bf16 v[106:109], v[174:177], v[212:215], v[106:109]
	v_mfma_f32_16x16x32_bf16 v[98:101], v[182:185], v[212:215], v[98:101]
	v_mfma_f32_16x16x32_bf16 v[90:93], v[174:177], v[220:223], v[90:93]
	v_mfma_f32_16x16x32_bf16 v[82:85], v[182:185], v[220:223], v[82:85]
	s_barrier
	s_add_i32 s60, s80, s22
	v_lshl_add_u64 v[224:225], v[224:225], 0, s[0:1]
	s_mov_b32 m0, s60
	ds_read_b128 v[190:193], v188 offset:49152
	ds_read_b128 v[194:197], v188 offset:50176
	ds_read_b128 v[198:201], v188 offset:51200
	ds_read_b128 v[202:205], v188 offset:52224
	ds_read_b128 v[208:211], v188 offset:53248
	ds_read_b128 v[212:215], v188 offset:54272
	ds_read_b128 v[216:219], v188 offset:55296
	ds_read_b128 v[220:223], v188 offset:56320
	global_load_lds_dwordx4 v[224:225], off
	s_add_i32 m0, s60, 0x2000
	s_add_u32 s58, s58, 0x40080
	v_lshl_add_u64 v[224:225], v[226:227], 0, s[0:1]
	s_addc_u32 s59, s59, 0
	s_add_i32 s60, s81, s22
	global_load_lds_dwordx4 v[224:225], off
	v_lshl_add_u64 v[224:225], s[58:59], 0, v[158:159]
	s_mov_b32 m0, s60
	s_nop 0
	global_load_lds_dwordx4 v[224:225], off
	v_lshl_add_u64 v[224:225], s[58:59], 0, v[154:155]
	s_add_i32 m0, s60, 0x2000
	s_nop 0
	global_load_lds_dwordx4 v[224:225], off
	v_lshl_add_u64 v[224:225], v[228:229], 0, s[0:1]
	s_mov_b32 m0, s69
	s_nop 0
	global_load_lds_dwordx4 v[224:225], off
	v_lshl_add_u64 v[224:225], v[230:231], 0, s[0:1]
	s_mov_b32 m0, s70
	s_nop 0
	global_load_lds_dwordx4 v[224:225], off
	s_waitcnt vmcnt(8)
	s_waitcnt lgkmcnt(0)
	s_barrier
	s_waitcnt lgkmcnt(0)
	v_mfma_f32_16x16x32_bf16 v[78:81], v[66:69], v[190:193], v[78:81]
	v_mfma_f32_16x16x32_bf16 v[62:65], v[74:77], v[190:193], v[62:65]
	v_mfma_f32_16x16x32_bf16 v[46:49], v[66:69], v[198:201], v[46:49]
	v_mfma_f32_16x16x32_bf16 v[38:41], v[74:77], v[198:201], v[38:41]
	v_mfma_f32_16x16x32_bf16 v[30:33], v[66:69], v[208:211], v[30:33]
	v_mfma_f32_16x16x32_bf16 v[22:25], v[74:77], v[208:211], v[22:25]
	v_mfma_f32_16x16x32_bf16 v[14:17], v[66:69], v[216:219], v[14:17]
	v_mfma_f32_16x16x32_bf16 v[6:9], v[74:77], v[216:219], v[6:9]
	v_mfma_f32_16x16x32_bf16 v[78:81], v[70:73], v[194:197], v[78:81]
	v_mfma_f32_16x16x32_bf16 v[62:65], v[146:149], v[194:197], v[62:65]
	v_mfma_f32_16x16x32_bf16 v[46:49], v[70:73], v[202:205], v[46:49]
	v_mfma_f32_16x16x32_bf16 v[38:41], v[146:149], v[202:205], v[38:41]
	v_mfma_f32_16x16x32_bf16 v[30:33], v[70:73], v[212:215], v[30:33]
	v_mfma_f32_16x16x32_bf16 v[22:25], v[146:149], v[212:215], v[22:25]
	v_mfma_f32_16x16x32_bf16 v[14:17], v[70:73], v[220:223], v[14:17]
	v_mfma_f32_16x16x32_bf16 v[6:9], v[146:149], v[220:223], v[6:9]
	v_mfma_f32_16x16x32_bf16 v[54:57], v[150:153], v[190:193], v[54:57]
	v_mfma_f32_16x16x32_bf16 v[74:77], v[174:177], v[194:197], v[54:57]
	v_mfma_f32_16x16x32_bf16 v[54:57], v[178:181], v[190:193], v[58:61]
	v_mfma_f32_16x16x32_bf16 v[42:45], v[150:153], v[198:201], v[42:45]
	v_mfma_f32_16x16x32_bf16 v[34:37], v[178:181], v[198:201], v[34:37]
	v_mfma_f32_16x16x32_bf16 v[26:29], v[150:153], v[208:211], v[26:29]
	v_mfma_f32_16x16x32_bf16 v[18:21], v[178:181], v[208:211], v[18:21]
	v_mfma_f32_16x16x32_bf16 v[10:13], v[150:153], v[216:219], v[10:13]
	v_mfma_f32_16x16x32_bf16 v[2:5], v[178:181], v[216:219], v[2:5]
	v_mfma_f32_16x16x32_bf16 v[58:61], v[182:185], v[194:197], v[54:57]
	v_mfma_f32_16x16x32_bf16 v[42:45], v[174:177], v[202:205], v[42:45]
	v_mfma_f32_16x16x32_bf16 v[34:37], v[182:185], v[202:205], v[34:37]
	v_mfma_f32_16x16x32_bf16 v[26:29], v[174:177], v[212:215], v[26:29]
	v_mfma_f32_16x16x32_bf16 v[18:21], v[182:185], v[212:215], v[18:21]
	v_mfma_f32_16x16x32_bf16 v[10:13], v[174:177], v[220:223], v[10:13]
	v_mfma_f32_16x16x32_bf16 v[2:5], v[182:185], v[220:223], v[2:5]
	s_barrier
	s_add_i32 s49, s49, 2
	s_add_u32 s56, s56, 0x100
	s_addc_u32 s57, s57, 0
	s_add_u32 s12, s12, 0x100
	s_addc_u32 s13, s13, 0
	s_cmp_gt_u32 s49, 13
	s_cbranch_scc1 .LBB0_310

.LBB0_387:
	s_ashr_i32 s65, s64, 31
	s_lshl_b64 s[12:13], s[64:65], 11
	v_lshl_add_u64 v[130:131], v[174:175], 0, s[12:13]
	s_lshl_b32 s12, s57, 12
	s_add_i32 s69, s90, -2
	s_and_b32 s65, s12, 0x1000
	s_lshl_b64 s[12:13], s[66:67], 10
	s_add_u32 s74, s74, 0x80
	s_addc_u32 s75, s75, 0
	s_add_u32 s67, s76, 0x100
	s_waitcnt lgkmcnt(0)
	v_lshl_add_u64 v[132:133], v[176:177], 0, s[12:13]
	s_addc_u32 s73, s77, 0
	s_mov_b32 s12, 0
	s_mov_b64 s[76:77], 0
	s_add_i32 s12, s12, 2
	s_add_u32 s13, s74, 0x80
	s_addc_u32 vcc_lo, s75, 0
	s_and_b64 s[76:77], s[76:77], exec
	s_cselect_b32 s77, s71, vcc_lo
	s_cselect_b32 s76, s70, s13
	s_cselect_b32 vcc_hi, s45, s73
	s_cselect_b32 vcc_lo, s44, s67
	s_add_i32 s13, 0, 0x10000
	v_add_u32_e32 v1, s13, v208
	s_add_i32 s88, 0, 0x14000
	ds_read_b128 v[134:137], v1
	ds_read_b128 v[138:141], v1 offset:1024
	ds_read_b128 v[142:145], v1 offset:2048
	ds_read_b128 v[146:149], v1 offset:3072
	v_add_u32_e32 v1, s88, v208
	ds_read_b128 v[150:153], v1
	ds_read_b128 v[154:157], v1 offset:1024
	ds_read_b128 v[158:161], v1 offset:2048
	ds_read_b128 v[182:185], v1 offset:3072
	v_lshl_add_u64 v[224:225], s[74:75], 0, v[178:179]
	s_add_i32 m0, s80, 0xc000
	ds_read_b128 v[186:189], v211
	ds_read_b128 v[190:193], v211 offset:1024
	ds_read_b128 v[194:197], v211 offset:2048
	ds_read_b128 v[198:201], v211 offset:3072
	ds_read_b128 v[202:205], v211 offset:4096
	ds_read_b128 v[212:215], v211 offset:5120
	ds_read_b128 v[216:219], v211 offset:6144
	ds_read_b128 v[220:223], v211 offset:7168
	global_load_lds_dwordx4 v[224:225], off
	v_lshl_add_u64 v[224:225], s[74:75], 0, v[180:181]
	s_add_i32 m0, s80, 0xe000
	s_nop 0
	global_load_lds_dwordx4 v[224:225], off
	s_waitcnt vmcnt(8)
	s_waitcnt lgkmcnt(0)
	s_barrier
	s_waitcnt lgkmcnt(0)
	v_mfma_f32_16x16x32_bf16 v[126:129], v[134:137], v[186:189], 0
	v_mfma_f32_16x16x32_bf16 v[122:125], v[142:145], v[186:189], 0
	v_mfma_f32_16x16x32_bf16 v[118:121], v[134:137], v[194:197], 0
	v_mfma_f32_16x16x32_bf16 v[114:117], v[142:145], v[194:197], 0
	v_mfma_f32_16x16x32_bf16 v[102:105], v[134:137], v[202:205], 0
	v_mfma_f32_16x16x32_bf16 v[98:101], v[142:145], v[202:205], 0
	v_mfma_f32_16x16x32_bf16 v[86:89], v[134:137], v[216:219], 0
	v_mfma_f32_16x16x32_bf16 v[82:85], v[142:145], v[216:219], 0
	v_mfma_f32_16x16x32_bf16 v[126:129], v[138:141], v[190:193], v[126:129]
	v_mfma_f32_16x16x32_bf16 v[122:125], v[146:149], v[190:193], v[122:125]
	v_mfma_f32_16x16x32_bf16 v[118:121], v[138:141], v[198:201], v[118:121]
	v_mfma_f32_16x16x32_bf16 v[114:117], v[146:149], v[198:201], v[114:117]
	v_mfma_f32_16x16x32_bf16 v[102:105], v[138:141], v[212:215], v[102:105]
	v_mfma_f32_16x16x32_bf16 v[98:101], v[146:149], v[212:215], v[98:101]
	v_mfma_f32_16x16x32_bf16 v[86:89], v[138:141], v[220:223], v[86:89]
	v_mfma_f32_16x16x32_bf16 v[82:85], v[146:149], v[220:223], v[82:85]
	v_mfma_f32_16x16x32_bf16 v[110:113], v[150:153], v[186:189], 0
	v_mfma_f32_16x16x32_bf16 v[106:109], v[158:161], v[186:189], 0
	v_mfma_f32_16x16x32_bf16 v[94:97], v[150:153], v[194:197], 0
	v_mfma_f32_16x16x32_bf16 v[90:93], v[158:161], v[194:197], 0
	v_mfma_f32_16x16x32_bf16 v[78:81], v[150:153], v[202:205], 0
	v_mfma_f32_16x16x32_bf16 v[74:77], v[158:161], v[202:205], 0
	v_mfma_f32_16x16x32_bf16 v[70:73], v[150:153], v[216:219], 0
	v_mfma_f32_16x16x32_bf16 v[66:69], v[158:161], v[216:219], 0
	v_mfma_f32_16x16x32_bf16 v[110:113], v[154:157], v[190:193], v[110:113]
	v_mfma_f32_16x16x32_bf16 v[106:109], v[182:185], v[190:193], v[106:109]
	v_mfma_f32_16x16x32_bf16 v[94:97], v[154:157], v[198:201], v[94:97]
	v_mfma_f32_16x16x32_bf16 v[90:93], v[182:185], v[198:201], v[90:93]
	v_mfma_f32_16x16x32_bf16 v[78:81], v[154:157], v[212:215], v[78:81]
	v_mfma_f32_16x16x32_bf16 v[74:77], v[182:185], v[212:215], v[74:77]
	v_mfma_f32_16x16x32_bf16 v[70:73], v[154:157], v[220:223], v[70:73]
	v_mfma_f32_16x16x32_bf16 v[66:69], v[182:185], v[220:223], v[66:69]
	s_barrier
	s_add_i32 s13, s13, s97
	v_lshl_add_u64 v[224:225], vcc, 0, v[168:169]
	s_mov_b32 m0, s13
	ds_read_b128 v[186:189], v211 offset:16384
	ds_read_b128 v[190:193], v211 offset:17408
	ds_read_b128 v[194:197], v211 offset:18432
	ds_read_b128 v[198:201], v211 offset:19456
	ds_read_b128 v[202:205], v211 offset:20480
	ds_read_b128 v[212:215], v211 offset:21504
	ds_read_b128 v[216:219], v211 offset:22528
	ds_read_b128 v[220:223], v211 offset:23552
	global_load_lds_dwordx4 v[224:225], off
	s_add_i32 m0, s13, 0x2000
	v_lshl_add_u64 v[226:227], vcc, 0, v[172:173]
	s_add_u32 vcc_lo, vcc_lo, s59
	s_addc_u32 vcc_hi, vcc_hi, 0
	s_add_i32 s13, s88, s97
	global_load_lds_dwordx4 v[226:227], off
	v_lshl_add_u64 v[228:229], vcc, 0, v[168:169]
	s_mov_b32 m0, s13
	v_lshl_add_u64 v[230:231], vcc, 0, v[172:173]
	global_load_lds_dwordx4 v[228:229], off
	s_add_i32 m0, s13, 0x2000
	v_lshl_add_u64 v[232:233], s[76:77], 0, v[166:167]
	global_load_lds_dwordx4 v[230:231], off
	s_mov_b32 m0, s80
	v_lshl_add_u64 v[242:243], s[76:77], 0, v[170:171]
	global_load_lds_dwordx4 v[232:233], off
	s_mov_b32 m0, s60
	s_nop 0
	global_load_lds_dwordx4 v[242:243], off
	s_waitcnt vmcnt(8)
	s_waitcnt lgkmcnt(0)
	s_barrier
	s_waitcnt lgkmcnt(0)
	v_mfma_f32_16x16x32_bf16 v[62:65], v[134:137], v[186:189], 0
	v_mfma_f32_16x16x32_bf16 v[58:61], v[142:145], v[186:189], 0
	v_mfma_f32_16x16x32_bf16 v[54:57], v[134:137], v[194:197], 0
	v_mfma_f32_16x16x32_bf16 v[50:53], v[142:145], v[194:197], 0
	v_mfma_f32_16x16x32_bf16 v[38:41], v[134:137], v[202:205], 0
	v_mfma_f32_16x16x32_bf16 v[34:37], v[142:145], v[202:205], 0
	v_mfma_f32_16x16x32_bf16 v[22:25], v[134:137], v[216:219], 0
	v_mfma_f32_16x16x32_bf16 v[18:21], v[142:145], v[216:219], 0
	v_mfma_f32_16x16x32_bf16 v[62:65], v[138:141], v[190:193], v[62:65]
	v_mfma_f32_16x16x32_bf16 v[58:61], v[146:149], v[190:193], v[58:61]
	v_mfma_f32_16x16x32_bf16 v[54:57], v[138:141], v[198:201], v[54:57]
	v_mfma_f32_16x16x32_bf16 v[50:53], v[146:149], v[198:201], v[50:53]
	v_mfma_f32_16x16x32_bf16 v[38:41], v[138:141], v[212:215], v[38:41]
	v_mfma_f32_16x16x32_bf16 v[34:37], v[146:149], v[212:215], v[34:37]
	v_mfma_f32_16x16x32_bf16 v[22:25], v[138:141], v[220:223], v[22:25]
	v_mfma_f32_16x16x32_bf16 v[18:21], v[146:149], v[220:223], v[18:21]
	v_mfma_f32_16x16x32_bf16 v[46:49], v[150:153], v[186:189], 0
	v_mfma_f32_16x16x32_bf16 v[42:45], v[158:161], v[186:189], 0
	v_mfma_f32_16x16x32_bf16 v[30:33], v[150:153], v[194:197], 0
	v_mfma_f32_16x16x32_bf16 v[26:29], v[158:161], v[194:197], 0
	v_mfma_f32_16x16x32_bf16 v[14:17], v[150:153], v[202:205], 0
	v_mfma_f32_16x16x32_bf16 v[10:13], v[158:161], v[202:205], 0
	v_mfma_f32_16x16x32_bf16 v[6:9], v[150:153], v[216:219], 0
	v_mfma_f32_16x16x32_bf16 v[2:5], v[158:161], v[216:219], 0
	v_mfma_f32_16x16x32_bf16 v[46:49], v[154:157], v[190:193], v[46:49]
	v_mfma_f32_16x16x32_bf16 v[42:45], v[182:185], v[190:193], v[42:45]
	v_mfma_f32_16x16x32_bf16 v[30:33], v[154:157], v[198:201], v[30:33]
	v_mfma_f32_16x16x32_bf16 v[26:29], v[182:185], v[198:201], v[26:29]
	v_mfma_f32_16x16x32_bf16 v[14:17], v[154:157], v[212:215], v[14:17]
	v_mfma_f32_16x16x32_bf16 v[10:13], v[182:185], v[212:215], v[10:13]
	v_mfma_f32_16x16x32_bf16 v[6:9], v[154:157], v[220:223], v[6:9]
	v_mfma_f32_16x16x32_bf16 v[2:5], v[182:185], v[220:223], v[2:5]
	s_barrier
	s_branch .Lpeel_mid_rs
.LBB0_388:
	s_add_i32 s12, s12, 2
	s_add_u32 s13, s74, 0x80
	s_addc_u32 vcc_lo, s75, 0
	s_and_b64 s[76:77], s[76:77], exec
	s_cselect_b32 s77, s71, vcc_lo
	s_cselect_b32 s76, s70, s13
	s_cselect_b32 vcc_hi, s45, s73
	s_cselect_b32 vcc_lo, s44, s67
	s_add_i32 s13, 0, 0x10000
	v_add_u32_e32 v1, s13, v208
	s_add_i32 s88, 0, 0x14000
	ds_read_b128 v[134:137], v1
	ds_read_b128 v[138:141], v1 offset:1024
	ds_read_b128 v[142:145], v1 offset:2048
	ds_read_b128 v[146:149], v1 offset:3072
	v_add_u32_e32 v1, s88, v208
	ds_read_b128 v[150:153], v1
	ds_read_b128 v[154:157], v1 offset:1024
	ds_read_b128 v[158:161], v1 offset:2048
	ds_read_b128 v[182:185], v1 offset:3072
	v_lshl_add_u64 v[224:225], s[74:75], 0, v[178:179]
	s_add_i32 m0, s80, 0xc000
	ds_read_b128 v[186:189], v211
	ds_read_b128 v[190:193], v211 offset:1024
	ds_read_b128 v[194:197], v211 offset:2048
	ds_read_b128 v[198:201], v211 offset:3072
	ds_read_b128 v[202:205], v211 offset:4096
	ds_read_b128 v[212:215], v211 offset:5120
	ds_read_b128 v[216:219], v211 offset:6144
	ds_read_b128 v[220:223], v211 offset:7168
	global_load_lds_dwordx4 v[224:225], off
	v_lshl_add_u64 v[224:225], s[74:75], 0, v[180:181]
	s_add_i32 m0, s80, 0xe000
	s_nop 0
	global_load_lds_dwordx4 v[224:225], off
	s_waitcnt vmcnt(8)
	s_waitcnt lgkmcnt(0)
	s_barrier
	s_waitcnt lgkmcnt(0)
	v_mfma_f32_16x16x32_bf16 v[126:129], v[134:137], v[186:189], v[126:129]
	v_mfma_f32_16x16x32_bf16 v[122:125], v[142:145], v[186:189], v[122:125]
	v_mfma_f32_16x16x32_bf16 v[118:121], v[134:137], v[194:197], v[118:121]
	v_mfma_f32_16x16x32_bf16 v[114:117], v[142:145], v[194:197], v[114:117]
	v_mfma_f32_16x16x32_bf16 v[102:105], v[134:137], v[202:205], v[102:105]
	v_mfma_f32_16x16x32_bf16 v[98:101], v[142:145], v[202:205], v[98:101]
	v_mfma_f32_16x16x32_bf16 v[86:89], v[134:137], v[216:219], v[86:89]
	v_mfma_f32_16x16x32_bf16 v[82:85], v[142:145], v[216:219], v[82:85]
	v_mfma_f32_16x16x32_bf16 v[126:129], v[138:141], v[190:193], v[126:129]
	v_mfma_f32_16x16x32_bf16 v[122:125], v[146:149], v[190:193], v[122:125]
	v_mfma_f32_16x16x32_bf16 v[118:121], v[138:141], v[198:201], v[118:121]
	v_mfma_f32_16x16x32_bf16 v[114:117], v[146:149], v[198:201], v[114:117]
	v_mfma_f32_16x16x32_bf16 v[102:105], v[138:141], v[212:215], v[102:105]
	v_mfma_f32_16x16x32_bf16 v[98:101], v[146:149], v[212:215], v[98:101]
	v_mfma_f32_16x16x32_bf16 v[86:89], v[138:141], v[220:223], v[86:89]
	v_mfma_f32_16x16x32_bf16 v[82:85], v[146:149], v[220:223], v[82:85]
	v_mfma_f32_16x16x32_bf16 v[110:113], v[150:153], v[186:189], v[110:113]
	v_mfma_f32_16x16x32_bf16 v[106:109], v[158:161], v[186:189], v[106:109]
	v_mfma_f32_16x16x32_bf16 v[94:97], v[150:153], v[194:197], v[94:97]
	v_mfma_f32_16x16x32_bf16 v[90:93], v[158:161], v[194:197], v[90:93]
	v_mfma_f32_16x16x32_bf16 v[78:81], v[150:153], v[202:205], v[78:81]
	v_mfma_f32_16x16x32_bf16 v[74:77], v[158:161], v[202:205], v[74:77]
	v_mfma_f32_16x16x32_bf16 v[70:73], v[150:153], v[216:219], v[70:73]
	v_mfma_f32_16x16x32_bf16 v[66:69], v[158:161], v[216:219], v[66:69]
	v_mfma_f32_16x16x32_bf16 v[110:113], v[154:157], v[190:193], v[110:113]
	v_mfma_f32_16x16x32_bf16 v[106:109], v[182:185], v[190:193], v[106:109]
	v_mfma_f32_16x16x32_bf16 v[94:97], v[154:157], v[198:201], v[94:97]
	v_mfma_f32_16x16x32_bf16 v[90:93], v[182:185], v[198:201], v[90:93]
	v_mfma_f32_16x16x32_bf16 v[78:81], v[154:157], v[212:215], v[78:81]
	v_mfma_f32_16x16x32_bf16 v[74:77], v[182:185], v[212:215], v[74:77]
	v_mfma_f32_16x16x32_bf16 v[70:73], v[154:157], v[220:223], v[70:73]
	v_mfma_f32_16x16x32_bf16 v[66:69], v[182:185], v[220:223], v[66:69]
	s_barrier
	s_add_i32 s13, s13, s97
	v_lshl_add_u64 v[224:225], vcc, 0, v[168:169]
	s_mov_b32 m0, s13
	ds_read_b128 v[186:189], v211 offset:16384
	ds_read_b128 v[190:193], v211 offset:17408
	ds_read_b128 v[194:197], v211 offset:18432
	ds_read_b128 v[198:201], v211 offset:19456
	ds_read_b128 v[202:205], v211 offset:20480
	ds_read_b128 v[212:215], v211 offset:21504
	ds_read_b128 v[216:219], v211 offset:22528
	ds_read_b128 v[220:223], v211 offset:23552
	global_load_lds_dwordx4 v[224:225], off
	s_add_i32 m0, s13, 0x2000
	v_lshl_add_u64 v[226:227], vcc, 0, v[172:173]
	s_add_u32 vcc_lo, vcc_lo, s59
	s_addc_u32 vcc_hi, vcc_hi, 0
	s_add_i32 s13, s88, s97
	global_load_lds_dwordx4 v[226:227], off
	v_lshl_add_u64 v[228:229], vcc, 0, v[168:169]
	s_mov_b32 m0, s13
	v_lshl_add_u64 v[230:231], vcc, 0, v[172:173]
	global_load_lds_dwordx4 v[228:229], off
	s_add_i32 m0, s13, 0x2000
	v_lshl_add_u64 v[232:233], s[76:77], 0, v[166:167]
	global_load_lds_dwordx4 v[230:231], off
	s_mov_b32 m0, s80
	v_lshl_add_u64 v[242:243], s[76:77], 0, v[170:171]
	global_load_lds_dwordx4 v[232:233], off
	s_mov_b32 m0, s60
	s_nop 0
	global_load_lds_dwordx4 v[242:243], off
	s_waitcnt vmcnt(8)
	s_waitcnt lgkmcnt(0)
	s_barrier
	s_waitcnt lgkmcnt(0)
	v_mfma_f32_16x16x32_bf16 v[62:65], v[134:137], v[186:189], v[62:65]
	v_mfma_f32_16x16x32_bf16 v[58:61], v[142:145], v[186:189], v[58:61]
	v_mfma_f32_16x16x32_bf16 v[54:57], v[134:137], v[194:197], v[54:57]
	v_mfma_f32_16x16x32_bf16 v[50:53], v[142:145], v[194:197], v[50:53]
	v_mfma_f32_16x16x32_bf16 v[38:41], v[134:137], v[202:205], v[38:41]
	v_mfma_f32_16x16x32_bf16 v[34:37], v[142:145], v[202:205], v[34:37]
	v_mfma_f32_16x16x32_bf16 v[22:25], v[134:137], v[216:219], v[22:25]
	v_mfma_f32_16x16x32_bf16 v[18:21], v[142:145], v[216:219], v[18:21]
	v_mfma_f32_16x16x32_bf16 v[62:65], v[138:141], v[190:193], v[62:65]
	v_mfma_f32_16x16x32_bf16 v[58:61], v[146:149], v[190:193], v[58:61]
	v_mfma_f32_16x16x32_bf16 v[54:57], v[138:141], v[198:201], v[54:57]
	v_mfma_f32_16x16x32_bf16 v[50:53], v[146:149], v[198:201], v[50:53]
	v_mfma_f32_16x16x32_bf16 v[38:41], v[138:141], v[212:215], v[38:41]
	v_mfma_f32_16x16x32_bf16 v[34:37], v[146:149], v[212:215], v[34:37]
	v_mfma_f32_16x16x32_bf16 v[22:25], v[138:141], v[220:223], v[22:25]
	v_mfma_f32_16x16x32_bf16 v[18:21], v[146:149], v[220:223], v[18:21]
	v_mfma_f32_16x16x32_bf16 v[46:49], v[150:153], v[186:189], v[46:49]
	v_mfma_f32_16x16x32_bf16 v[42:45], v[158:161], v[186:189], v[42:45]
	v_mfma_f32_16x16x32_bf16 v[30:33], v[150:153], v[194:197], v[30:33]
	v_mfma_f32_16x16x32_bf16 v[26:29], v[158:161], v[194:197], v[26:29]
	v_mfma_f32_16x16x32_bf16 v[14:17], v[150:153], v[202:205], v[14:17]
	v_mfma_f32_16x16x32_bf16 v[10:13], v[158:161], v[202:205], v[10:13]
	v_mfma_f32_16x16x32_bf16 v[6:9], v[150:153], v[216:219], v[6:9]
	v_mfma_f32_16x16x32_bf16 v[2:5], v[158:161], v[216:219], v[2:5]
	v_mfma_f32_16x16x32_bf16 v[46:49], v[154:157], v[190:193], v[46:49]
	v_mfma_f32_16x16x32_bf16 v[42:45], v[182:185], v[190:193], v[42:45]
	v_mfma_f32_16x16x32_bf16 v[30:33], v[154:157], v[198:201], v[30:33]
	v_mfma_f32_16x16x32_bf16 v[26:29], v[182:185], v[198:201], v[26:29]
	v_mfma_f32_16x16x32_bf16 v[14:17], v[154:157], v[212:215], v[14:17]
	v_mfma_f32_16x16x32_bf16 v[10:13], v[182:185], v[212:215], v[10:13]
	v_mfma_f32_16x16x32_bf16 v[6:9], v[154:157], v[220:223], v[6:9]
	v_mfma_f32_16x16x32_bf16 v[2:5], v[182:185], v[220:223], v[2:5]
	s_barrier
.Lpeel_mid_rs:
	s_add_i32 s13, 0, 0x18000
	v_add_u32_e32 v1, s13, v208
	s_add_i32 s88, 0, 0x1c000
	ds_read_b128 v[134:137], v1
	ds_read_b128 v[138:141], v1 offset:1024
	ds_read_b128 v[142:145], v1 offset:2048
	ds_read_b128 v[146:149], v1 offset:3072
	v_add_u32_e32 v1, s88, v208
	ds_read_b128 v[150:153], v1
	ds_read_b128 v[154:157], v1 offset:1024
	ds_read_b128 v[158:161], v1 offset:2048
	ds_read_b128 v[182:185], v1 offset:3072
	s_add_u32 s76, s76, s56
	s_addc_u32 s77, s77, 0
	s_mov_b32 m0, s61
	v_lshl_add_u64 v[244:245], s[76:77], 0, v[166:167]
	ds_read_b128 v[186:189], v211 offset:32768
	ds_read_b128 v[190:193], v211 offset:33792
	ds_read_b128 v[194:197], v211 offset:34816
	ds_read_b128 v[198:201], v211 offset:35840
	ds_read_b128 v[202:205], v211 offset:36864
	ds_read_b128 v[212:215], v211 offset:37888
	ds_read_b128 v[216:219], v211 offset:38912
	ds_read_b128 v[220:223], v211 offset:39936
	global_load_lds_dwordx4 v[244:245], off
	v_lshl_add_u64 v[244:245], s[76:77], 0, v[170:171]
	s_mov_b32 m0, s83
	s_nop 0
	global_load_lds_dwordx4 v[244:245], off
	s_waitcnt vmcnt(8)
	s_waitcnt lgkmcnt(0)
	s_barrier
	s_waitcnt lgkmcnt(0)
	v_mfma_f32_16x16x32_bf16 v[126:129], v[134:137], v[186:189], v[126:129]
	v_mfma_f32_16x16x32_bf16 v[122:125], v[142:145], v[186:189], v[122:125]
	v_mfma_f32_16x16x32_bf16 v[118:121], v[134:137], v[194:197], v[118:121]
	v_mfma_f32_16x16x32_bf16 v[114:117], v[142:145], v[194:197], v[114:117]
	v_mfma_f32_16x16x32_bf16 v[102:105], v[134:137], v[202:205], v[102:105]
	v_mfma_f32_16x16x32_bf16 v[98:101], v[142:145], v[202:205], v[98:101]
	v_mfma_f32_16x16x32_bf16 v[86:89], v[134:137], v[216:219], v[86:89]
	v_mfma_f32_16x16x32_bf16 v[82:85], v[142:145], v[216:219], v[82:85]
	v_mfma_f32_16x16x32_bf16 v[126:129], v[138:141], v[190:193], v[126:129]
	v_mfma_f32_16x16x32_bf16 v[122:125], v[146:149], v[190:193], v[122:125]
	v_mfma_f32_16x16x32_bf16 v[118:121], v[138:141], v[198:201], v[118:121]
	v_mfma_f32_16x16x32_bf16 v[114:117], v[146:149], v[198:201], v[114:117]
	v_mfma_f32_16x16x32_bf16 v[102:105], v[138:141], v[212:215], v[102:105]
	v_mfma_f32_16x16x32_bf16 v[98:101], v[146:149], v[212:215], v[98:101]
	v_mfma_f32_16x16x32_bf16 v[86:89], v[138:141], v[220:223], v[86:89]
	v_mfma_f32_16x16x32_bf16 v[82:85], v[146:149], v[220:223], v[82:85]
	v_mfma_f32_16x16x32_bf16 v[110:113], v[150:153], v[186:189], v[110:113]
	v_mfma_f32_16x16x32_bf16 v[106:109], v[158:161], v[186:189], v[106:109]
	v_mfma_f32_16x16x32_bf16 v[94:97], v[150:153], v[194:197], v[94:97]
	v_mfma_f32_16x16x32_bf16 v[90:93], v[158:161], v[194:197], v[90:93]
	v_mfma_f32_16x16x32_bf16 v[78:81], v[150:153], v[202:205], v[78:81]
	v_mfma_f32_16x16x32_bf16 v[74:77], v[158:161], v[202:205], v[74:77]
	v_mfma_f32_16x16x32_bf16 v[70:73], v[150:153], v[216:219], v[70:73]
	v_mfma_f32_16x16x32_bf16 v[66:69], v[158:161], v[216:219], v[66:69]
	v_mfma_f32_16x16x32_bf16 v[110:113], v[154:157], v[190:193], v[110:113]
	v_mfma_f32_16x16x32_bf16 v[106:109], v[182:185], v[190:193], v[106:109]
	v_mfma_f32_16x16x32_bf16 v[94:97], v[154:157], v[198:201], v[94:97]
	v_mfma_f32_16x16x32_bf16 v[90:93], v[182:185], v[198:201], v[90:93]
	v_mfma_f32_16x16x32_bf16 v[78:81], v[154:157], v[212:215], v[78:81]
	v_mfma_f32_16x16x32_bf16 v[74:77], v[182:185], v[212:215], v[74:77]
	v_mfma_f32_16x16x32_bf16 v[70:73], v[154:157], v[220:223], v[70:73]
	v_mfma_f32_16x16x32_bf16 v[66:69], v[182:185], v[220:223], v[66:69]
	s_barrier
	s_add_i32 s13, s13, s97
	v_lshl_add_u64 v[224:225], v[224:225], 0, s[0:1]
	s_mov_b32 m0, s13
	ds_read_b128 v[186:189], v211 offset:49152
	ds_read_b128 v[190:193], v211 offset:50176
	ds_read_b128 v[194:197], v211 offset:51200
	ds_read_b128 v[198:201], v211 offset:52224
	ds_read_b128 v[202:205], v211 offset:53248
	ds_read_b128 v[212:215], v211 offset:54272
	ds_read_b128 v[216:219], v211 offset:55296
	ds_read_b128 v[220:223], v211 offset:56320
	global_load_lds_dwordx4 v[224:225], off
	v_lshl_add_u64 v[224:225], v[226:227], 0, s[0:1]
	s_add_i32 m0, s13, 0x2000
	s_add_i32 s13, s88, s97
	global_load_lds_dwordx4 v[224:225], off
	v_lshl_add_u64 v[224:225], v[228:229], 0, s[0:1]
	s_mov_b32 m0, s13
	s_nop 0
	global_load_lds_dwordx4 v[224:225], off
	v_lshl_add_u64 v[224:225], v[230:231], 0, s[0:1]
	s_add_i32 m0, s13, 0x2000
	s_nop 0
	global_load_lds_dwordx4 v[224:225], off
	v_lshl_add_u64 v[224:225], v[232:233], 0, s[0:1]
	s_mov_b32 m0, s2
	s_nop 0
	global_load_lds_dwordx4 v[224:225], off
	v_lshl_add_u64 v[224:225], v[242:243], 0, s[0:1]
	s_mov_b32 m0, s86
	s_nop 0
	global_load_lds_dwordx4 v[224:225], off
	s_waitcnt vmcnt(8)
	s_waitcnt lgkmcnt(0)
	s_barrier
	s_waitcnt lgkmcnt(0)
	v_mfma_f32_16x16x32_bf16 v[62:65], v[134:137], v[186:189], v[62:65]
	v_mfma_f32_16x16x32_bf16 v[58:61], v[142:145], v[186:189], v[58:61]
	v_mfma_f32_16x16x32_bf16 v[54:57], v[134:137], v[194:197], v[54:57]
	v_mfma_f32_16x16x32_bf16 v[50:53], v[142:145], v[194:197], v[50:53]
	v_mfma_f32_16x16x32_bf16 v[38:41], v[134:137], v[202:205], v[38:41]
	v_mfma_f32_16x16x32_bf16 v[34:37], v[142:145], v[202:205], v[34:37]
	v_mfma_f32_16x16x32_bf16 v[22:25], v[134:137], v[216:219], v[22:25]
	v_mfma_f32_16x16x32_bf16 v[18:21], v[142:145], v[216:219], v[18:21]
	v_mfma_f32_16x16x32_bf16 v[62:65], v[138:141], v[190:193], v[62:65]
	v_mfma_f32_16x16x32_bf16 v[58:61], v[146:149], v[190:193], v[58:61]
	v_mfma_f32_16x16x32_bf16 v[54:57], v[138:141], v[198:201], v[54:57]
	v_mfma_f32_16x16x32_bf16 v[50:53], v[146:149], v[198:201], v[50:53]
	v_mfma_f32_16x16x32_bf16 v[38:41], v[138:141], v[212:215], v[38:41]
	v_mfma_f32_16x16x32_bf16 v[34:37], v[146:149], v[212:215], v[34:37]
	v_mfma_f32_16x16x32_bf16 v[22:25], v[138:141], v[220:223], v[22:25]
	v_mfma_f32_16x16x32_bf16 v[18:21], v[146:149], v[220:223], v[18:21]
	v_mfma_f32_16x16x32_bf16 v[46:49], v[150:153], v[186:189], v[46:49]
	v_mfma_f32_16x16x32_bf16 v[42:45], v[158:161], v[186:189], v[42:45]
	v_mfma_f32_16x16x32_bf16 v[30:33], v[150:153], v[194:197], v[30:33]
	v_mfma_f32_16x16x32_bf16 v[26:29], v[158:161], v[194:197], v[26:29]
	v_mfma_f32_16x16x32_bf16 v[14:17], v[150:153], v[202:205], v[14:17]
	v_mfma_f32_16x16x32_bf16 v[10:13], v[158:161], v[202:205], v[10:13]
	v_mfma_f32_16x16x32_bf16 v[6:9], v[150:153], v[216:219], v[6:9]
	v_mfma_f32_16x16x32_bf16 v[2:5], v[158:161], v[216:219], v[2:5]
	v_mfma_f32_16x16x32_bf16 v[46:49], v[154:157], v[190:193], v[46:49]
	v_mfma_f32_16x16x32_bf16 v[42:45], v[182:185], v[190:193], v[42:45]
	v_mfma_f32_16x16x32_bf16 v[30:33], v[154:157], v[198:201], v[30:33]
	v_mfma_f32_16x16x32_bf16 v[26:29], v[182:185], v[198:201], v[26:29]
	v_mfma_f32_16x16x32_bf16 v[14:17], v[154:157], v[212:215], v[14:17]
	v_mfma_f32_16x16x32_bf16 v[10:13], v[182:185], v[212:215], v[10:13]
	v_mfma_f32_16x16x32_bf16 v[6:9], v[154:157], v[220:223], v[6:9]
	v_mfma_f32_16x16x32_bf16 v[2:5], v[182:185], v[220:223], v[2:5]
	s_barrier
	s_add_u32 s74, s74, 0x100
	s_addc_u32 s75, s75, 0
	s_add_u32 s67, s67, 0x100
	s_addc_u32 s73, s73, 0
	s_cmp_ge_i32 s12, s90
	s_cbranch_scc1 .LBB0_396

.LBB0_871:
	s_ashr_i32 s55, s54, 31
	s_lshl_b64 s[12:13], s[54:55], 19
	s_add_u32 s56, s8, s12
	s_addc_u32 s57, s9, s13
	s_and_b64 s[12:13], exec, s[42:43]
	s_cselect_b32 s7, s63, s57
	s_cselect_b32 s45, s62, s56
	s_ashr_i32 s53, s52, 31
	s_lshl_b64 s[12:13], s[52:53], 19
	s_add_u32 s58, s24, s12
	s_addc_u32 s59, s25, s13
	s_and_b64 s[12:13], exec, s[42:43]
	s_cselect_b32 s61, s65, s59
	s_cselect_b32 s75, s64, s58
	s_lshl_b64 s[12:13], s[54:55], 11
	v_lshl_add_u64 v[130:131], v[164:165], 0, s[12:13]
	s_lshl_b32 s12, s74, 12
	s_and_b32 s55, s12, 0x1000
	s_lshl_b64 s[12:13], s[52:53], 10
	v_lshl_add_u64 v[132:133], v[166:167], 0, s[12:13]
	v_readlane_b32 s12, v253, 43
	v_readlane_b32 s13, v253, 44
	s_or_b64 s[42:43], s[42:43], s[12:13]
	s_add_u32 s62, s62, 0x40080
	s_addc_u32 s63, s63, 0
	s_add_u32 s12, s64, 0x100
	s_addc_u32 s13, s65, 0
	s_mov_b32 s53, -2
	s_add_i32 s55, s73, s55
	s_mov_b64 s[64:65], -1
	s_add_u32 s66, s62, 0xfffc0080
	s_addc_u32 s67, s63, -1
	s_and_b64 s[64:65], s[64:65], exec
	s_cselect_b32 s67, s67, s7
	s_cselect_b32 s66, s66, s45
	s_cselect_b32 s65, s13, s61
	s_cselect_b32 s64, s12, s75
	s_add_i32 s76, 0, 0x10000
	s_add_i32 s78, 0, 0x14000
	v_add_u32_e32 v146, s76, v169
	v_add_u32_e32 v190, s78, v169
	ds_read_b128 v[134:137], v146
	ds_read_b128 v[138:141], v146 offset:1024
	ds_read_b128 v[142:145], v146 offset:2048
	ds_read_b128 v[146:149], v146 offset:3072
	ds_read_b128 v[150:153], v190
	ds_read_b128 v[182:185], v190 offset:1024
	ds_read_b128 v[186:189], v190 offset:2048
	ds_read_b128 v[190:193], v190 offset:3072
	v_lshl_add_u64 v[226:227], s[62:63], 0, v[178:179]
	s_add_i32 m0, s22, 0xc000
	ds_read_b128 v[194:197], v250
	ds_read_b128 v[198:201], v250 offset:1024
	ds_read_b128 v[202:205], v250 offset:2048
	ds_read_b128 v[206:209], v250 offset:3072
	ds_read_b128 v[210:213], v250 offset:4096
	ds_read_b128 v[214:217], v250 offset:5120
	ds_read_b128 v[218:221], v250 offset:6144
	ds_read_b128 v[222:225], v250 offset:7168
	global_load_lds_dwordx4 v[226:227], off
	v_lshl_add_u64 v[226:227], s[62:63], 0, v[180:181]
	s_add_i32 m0, s22, 0xe000
	s_nop 0
	global_load_lds_dwordx4 v[226:227], off
	s_waitcnt vmcnt(8)
	s_waitcnt lgkmcnt(0)
	s_barrier
	s_waitcnt lgkmcnt(0)
	v_mfma_f32_16x16x32_bf16 v[62:65], v[134:137], v[194:197], 0
	v_mfma_f32_16x16x32_bf16 v[58:61], v[142:145], v[194:197], 0
	v_mfma_f32_16x16x32_bf16 v[54:57], v[134:137], v[202:205], 0
	v_mfma_f32_16x16x32_bf16 v[50:53], v[142:145], v[202:205], 0
	v_mfma_f32_16x16x32_bf16 v[46:49], v[134:137], v[210:213], 0
	v_mfma_f32_16x16x32_bf16 v[42:45], v[142:145], v[210:213], 0
	v_mfma_f32_16x16x32_bf16 v[38:41], v[134:137], v[218:221], 0
	v_mfma_f32_16x16x32_bf16 v[34:37], v[142:145], v[218:221], 0
	v_mfma_f32_16x16x32_bf16 v[62:65], v[138:141], v[198:201], v[62:65]
	v_mfma_f32_16x16x32_bf16 v[58:61], v[146:149], v[198:201], v[58:61]
	v_mfma_f32_16x16x32_bf16 v[54:57], v[138:141], v[206:209], v[54:57]
	v_mfma_f32_16x16x32_bf16 v[50:53], v[146:149], v[206:209], v[50:53]
	v_mfma_f32_16x16x32_bf16 v[46:49], v[138:141], v[214:217], v[46:49]
	v_mfma_f32_16x16x32_bf16 v[42:45], v[146:149], v[214:217], v[42:45]
	v_mfma_f32_16x16x32_bf16 v[38:41], v[138:141], v[222:225], v[38:41]
	v_mfma_f32_16x16x32_bf16 v[34:37], v[146:149], v[222:225], v[34:37]
	v_mfma_f32_16x16x32_bf16 v[126:129], v[150:153], v[194:197], 0
	v_mfma_f32_16x16x32_bf16 v[122:125], v[186:189], v[194:197], 0
	v_mfma_f32_16x16x32_bf16 v[118:121], v[150:153], v[202:205], 0
	v_mfma_f32_16x16x32_bf16 v[114:117], v[186:189], v[202:205], 0
	v_mfma_f32_16x16x32_bf16 v[110:113], v[150:153], v[210:213], 0
	v_mfma_f32_16x16x32_bf16 v[106:109], v[186:189], v[210:213], 0
	v_mfma_f32_16x16x32_bf16 v[102:105], v[150:153], v[218:221], 0
	v_mfma_f32_16x16x32_bf16 v[98:101], v[186:189], v[218:221], 0
	v_mfma_f32_16x16x32_bf16 v[126:129], v[182:185], v[198:201], v[126:129]
	v_mfma_f32_16x16x32_bf16 v[122:125], v[190:193], v[198:201], v[122:125]
	v_mfma_f32_16x16x32_bf16 v[118:121], v[182:185], v[206:209], v[118:121]
	v_mfma_f32_16x16x32_bf16 v[114:117], v[190:193], v[206:209], v[114:117]
	v_mfma_f32_16x16x32_bf16 v[110:113], v[182:185], v[214:217], v[110:113]
	v_mfma_f32_16x16x32_bf16 v[106:109], v[190:193], v[214:217], v[106:109]
	v_mfma_f32_16x16x32_bf16 v[102:105], v[182:185], v[222:225], v[102:105]
	v_mfma_f32_16x16x32_bf16 v[98:101], v[190:193], v[222:225], v[98:101]
	s_barrier
	s_add_i32 s76, s76, s16
	v_lshl_add_u64 v[226:227], s[64:65], 0, v[156:157]
	s_mov_b32 m0, s76
	ds_read_b128 v[194:197], v250 offset:16384
	ds_read_b128 v[198:201], v250 offset:17408
	ds_read_b128 v[202:205], v250 offset:18432
	ds_read_b128 v[206:209], v250 offset:19456
	ds_read_b128 v[210:213], v250 offset:20480
	ds_read_b128 v[214:217], v250 offset:21504
	ds_read_b128 v[218:221], v250 offset:22528
	ds_read_b128 v[222:225], v250 offset:23552
	global_load_lds_dwordx4 v[226:227], off
	s_add_i32 m0, s76, 0x2000
	s_add_u32 s76, s64, 0x40000
	v_lshl_add_u64 v[228:229], s[64:65], 0, v[160:161]
	s_addc_u32 s77, s65, 0
	s_add_i32 s78, s78, s16
	global_load_lds_dwordx4 v[228:229], off
	v_lshl_add_u64 v[230:231], s[76:77], 0, v[156:157]
	s_mov_b32 m0, s78
	v_lshl_add_u64 v[232:233], s[66:67], 0, v[158:159]
	global_load_lds_dwordx4 v[230:231], off
	v_lshl_add_u64 v[230:231], s[76:77], 0, v[160:161]
	s_add_i32 m0, s78, 0x2000
	s_nop 0
	global_load_lds_dwordx4 v[230:231], off
	v_lshl_add_u64 v[230:231], s[66:67], 0, v[154:155]
	s_mov_b32 m0, s22
	s_nop 0
	global_load_lds_dwordx4 v[230:231], off
	s_mov_b32 m0, s23
	s_nop 0
	global_load_lds_dwordx4 v[232:233], off
	s_waitcnt vmcnt(8)
	s_waitcnt lgkmcnt(0)
	s_barrier
	s_waitcnt lgkmcnt(0)
	v_mfma_f32_16x16x32_bf16 v[30:33], v[134:137], v[194:197], 0
	v_mfma_f32_16x16x32_bf16 v[26:29], v[142:145], v[194:197], 0
	v_mfma_f32_16x16x32_bf16 v[22:25], v[134:137], v[202:205], 0
	v_mfma_f32_16x16x32_bf16 v[18:21], v[142:145], v[202:205], 0
	v_mfma_f32_16x16x32_bf16 v[14:17], v[134:137], v[210:213], 0
	v_mfma_f32_16x16x32_bf16 v[10:13], v[142:145], v[210:213], 0
	v_mfma_f32_16x16x32_bf16 v[6:9], v[134:137], v[218:221], 0
	v_mfma_f32_16x16x32_bf16 v[2:5], v[142:145], v[218:221], 0
	v_mfma_f32_16x16x32_bf16 v[30:33], v[138:141], v[198:201], v[30:33]
	v_mfma_f32_16x16x32_bf16 v[26:29], v[146:149], v[198:201], v[26:29]
	v_mfma_f32_16x16x32_bf16 v[22:25], v[138:141], v[206:209], v[22:25]
	v_mfma_f32_16x16x32_bf16 v[18:21], v[146:149], v[206:209], v[18:21]
	v_mfma_f32_16x16x32_bf16 v[14:17], v[138:141], v[214:217], v[14:17]
	v_mfma_f32_16x16x32_bf16 v[10:13], v[146:149], v[214:217], v[10:13]
	v_mfma_f32_16x16x32_bf16 v[6:9], v[138:141], v[222:225], v[6:9]
	v_mfma_f32_16x16x32_bf16 v[2:5], v[146:149], v[222:225], v[2:5]
	v_mfma_f32_16x16x32_bf16 v[94:97], v[150:153], v[194:197], 0
	v_mfma_f32_16x16x32_bf16 v[90:93], v[186:189], v[194:197], 0
	v_mfma_f32_16x16x32_bf16 v[86:89], v[150:153], v[202:205], 0
	v_mfma_f32_16x16x32_bf16 v[82:85], v[186:189], v[202:205], 0
	v_mfma_f32_16x16x32_bf16 v[78:81], v[150:153], v[210:213], 0
	v_mfma_f32_16x16x32_bf16 v[74:77], v[186:189], v[210:213], 0
	v_mfma_f32_16x16x32_bf16 v[70:73], v[150:153], v[218:221], 0
	v_mfma_f32_16x16x32_bf16 v[66:69], v[186:189], v[218:221], 0
	v_mfma_f32_16x16x32_bf16 v[94:97], v[182:185], v[198:201], v[94:97]
	v_mfma_f32_16x16x32_bf16 v[90:93], v[190:193], v[198:201], v[90:93]
	v_mfma_f32_16x16x32_bf16 v[86:89], v[182:185], v[206:209], v[86:89]
	v_mfma_f32_16x16x32_bf16 v[82:85], v[190:193], v[206:209], v[82:85]
	v_mfma_f32_16x16x32_bf16 v[78:81], v[182:185], v[214:217], v[78:81]
	v_mfma_f32_16x16x32_bf16 v[74:77], v[190:193], v[214:217], v[74:77]
	v_mfma_f32_16x16x32_bf16 v[70:73], v[182:185], v[222:225], v[70:73]
	v_mfma_f32_16x16x32_bf16 v[66:69], v[190:193], v[222:225], v[66:69]
	s_barrier
	s_branch .Lpeel_mid_st
.LBB0_872:
	s_add_u32 s66, s62, 0xfffc0080
	s_addc_u32 s67, s63, -1
	s_and_b64 s[64:65], s[64:65], exec
	s_cselect_b32 s67, s67, s7
	s_cselect_b32 s66, s66, s45
	s_cselect_b32 s65, s13, s61
	s_cselect_b32 s64, s12, s75
	s_add_i32 s76, 0, 0x10000
	s_add_i32 s78, 0, 0x14000
	v_add_u32_e32 v146, s76, v169
	v_add_u32_e32 v190, s78, v169
	ds_read_b128 v[134:137], v146
	ds_read_b128 v[138:141], v146 offset:1024
	ds_read_b128 v[142:145], v146 offset:2048
	ds_read_b128 v[146:149], v146 offset:3072
	ds_read_b128 v[150:153], v190
	ds_read_b128 v[182:185], v190 offset:1024
	ds_read_b128 v[186:189], v190 offset:2048
	ds_read_b128 v[190:193], v190 offset:3072
	v_lshl_add_u64 v[226:227], s[62:63], 0, v[178:179]
	s_add_i32 m0, s22, 0xc000
	ds_read_b128 v[194:197], v250
	ds_read_b128 v[198:201], v250 offset:1024
	ds_read_b128 v[202:205], v250 offset:2048
	ds_read_b128 v[206:209], v250 offset:3072
	ds_read_b128 v[210:213], v250 offset:4096
	ds_read_b128 v[214:217], v250 offset:5120
	ds_read_b128 v[218:221], v250 offset:6144
	ds_read_b128 v[222:225], v250 offset:7168
	global_load_lds_dwordx4 v[226:227], off
	v_lshl_add_u64 v[226:227], s[62:63], 0, v[180:181]
	s_add_i32 m0, s22, 0xe000
	s_nop 0
	global_load_lds_dwordx4 v[226:227], off
	s_waitcnt vmcnt(8)
	s_waitcnt lgkmcnt(0)
	s_barrier
	s_waitcnt lgkmcnt(0)
	v_mfma_f32_16x16x32_bf16 v[62:65], v[134:137], v[194:197], v[62:65]
	v_mfma_f32_16x16x32_bf16 v[58:61], v[142:145], v[194:197], v[58:61]
	v_mfma_f32_16x16x32_bf16 v[54:57], v[134:137], v[202:205], v[54:57]
	v_mfma_f32_16x16x32_bf16 v[50:53], v[142:145], v[202:205], v[50:53]
	v_mfma_f32_16x16x32_bf16 v[46:49], v[134:137], v[210:213], v[46:49]
	v_mfma_f32_16x16x32_bf16 v[42:45], v[142:145], v[210:213], v[42:45]
	v_mfma_f32_16x16x32_bf16 v[38:41], v[134:137], v[218:221], v[38:41]
	v_mfma_f32_16x16x32_bf16 v[34:37], v[142:145], v[218:221], v[34:37]
	v_mfma_f32_16x16x32_bf16 v[62:65], v[138:141], v[198:201], v[62:65]
	v_mfma_f32_16x16x32_bf16 v[58:61], v[146:149], v[198:201], v[58:61]
	v_mfma_f32_16x16x32_bf16 v[54:57], v[138:141], v[206:209], v[54:57]
	v_mfma_f32_16x16x32_bf16 v[50:53], v[146:149], v[206:209], v[50:53]
	v_mfma_f32_16x16x32_bf16 v[46:49], v[138:141], v[214:217], v[46:49]
	v_mfma_f32_16x16x32_bf16 v[42:45], v[146:149], v[214:217], v[42:45]
	v_mfma_f32_16x16x32_bf16 v[38:41], v[138:141], v[222:225], v[38:41]
	v_mfma_f32_16x16x32_bf16 v[34:37], v[146:149], v[222:225], v[34:37]
	v_mfma_f32_16x16x32_bf16 v[126:129], v[150:153], v[194:197], v[126:129]
	v_mfma_f32_16x16x32_bf16 v[122:125], v[186:189], v[194:197], v[122:125]
	v_mfma_f32_16x16x32_bf16 v[118:121], v[150:153], v[202:205], v[118:121]
	v_mfma_f32_16x16x32_bf16 v[114:117], v[186:189], v[202:205], v[114:117]
	v_mfma_f32_16x16x32_bf16 v[110:113], v[150:153], v[210:213], v[110:113]
	v_mfma_f32_16x16x32_bf16 v[106:109], v[186:189], v[210:213], v[106:109]
	v_mfma_f32_16x16x32_bf16 v[102:105], v[150:153], v[218:221], v[102:105]
	v_mfma_f32_16x16x32_bf16 v[98:101], v[186:189], v[218:221], v[98:101]
	v_mfma_f32_16x16x32_bf16 v[126:129], v[182:185], v[198:201], v[126:129]
	v_mfma_f32_16x16x32_bf16 v[122:125], v[190:193], v[198:201], v[122:125]
	v_mfma_f32_16x16x32_bf16 v[118:121], v[182:185], v[206:209], v[118:121]
	v_mfma_f32_16x16x32_bf16 v[114:117], v[190:193], v[206:209], v[114:117]
	v_mfma_f32_16x16x32_bf16 v[110:113], v[182:185], v[214:217], v[110:113]
	v_mfma_f32_16x16x32_bf16 v[106:109], v[190:193], v[214:217], v[106:109]
	v_mfma_f32_16x16x32_bf16 v[102:105], v[182:185], v[222:225], v[102:105]
	v_mfma_f32_16x16x32_bf16 v[98:101], v[190:193], v[222:225], v[98:101]
	s_barrier
	s_add_i32 s76, s76, s16
	v_lshl_add_u64 v[226:227], s[64:65], 0, v[156:157]
	s_mov_b32 m0, s76
	ds_read_b128 v[194:197], v250 offset:16384
	ds_read_b128 v[198:201], v250 offset:17408
	ds_read_b128 v[202:205], v250 offset:18432
	ds_read_b128 v[206:209], v250 offset:19456
	ds_read_b128 v[210:213], v250 offset:20480
	ds_read_b128 v[214:217], v250 offset:21504
	ds_read_b128 v[218:221], v250 offset:22528
	ds_read_b128 v[222:225], v250 offset:23552
	global_load_lds_dwordx4 v[226:227], off
	s_add_i32 m0, s76, 0x2000
	s_add_u32 s76, s64, 0x40000
	v_lshl_add_u64 v[228:229], s[64:65], 0, v[160:161]
	s_addc_u32 s77, s65, 0
	s_add_i32 s78, s78, s16
	global_load_lds_dwordx4 v[228:229], off
	v_lshl_add_u64 v[230:231], s[76:77], 0, v[156:157]
	s_mov_b32 m0, s78
	v_lshl_add_u64 v[232:233], s[66:67], 0, v[158:159]
	global_load_lds_dwordx4 v[230:231], off
	v_lshl_add_u64 v[230:231], s[76:77], 0, v[160:161]
	s_add_i32 m0, s78, 0x2000
	s_nop 0
	global_load_lds_dwordx4 v[230:231], off
	v_lshl_add_u64 v[230:231], s[66:67], 0, v[154:155]
	s_mov_b32 m0, s22
	s_nop 0
	global_load_lds_dwordx4 v[230:231], off
	s_mov_b32 m0, s23
	s_nop 0
	global_load_lds_dwordx4 v[232:233], off
	s_waitcnt vmcnt(8)
	s_waitcnt lgkmcnt(0)
	s_barrier
	s_waitcnt lgkmcnt(0)
	v_mfma_f32_16x16x32_bf16 v[30:33], v[134:137], v[194:197], v[30:33]
	v_mfma_f32_16x16x32_bf16 v[26:29], v[142:145], v[194:197], v[26:29]
	v_mfma_f32_16x16x32_bf16 v[22:25], v[134:137], v[202:205], v[22:25]
	v_mfma_f32_16x16x32_bf16 v[18:21], v[142:145], v[202:205], v[18:21]
	v_mfma_f32_16x16x32_bf16 v[14:17], v[134:137], v[210:213], v[14:17]
	v_mfma_f32_16x16x32_bf16 v[10:13], v[142:145], v[210:213], v[10:13]
	v_mfma_f32_16x16x32_bf16 v[6:9], v[134:137], v[218:221], v[6:9]
	v_mfma_f32_16x16x32_bf16 v[2:5], v[142:145], v[218:221], v[2:5]
	v_mfma_f32_16x16x32_bf16 v[30:33], v[138:141], v[198:201], v[30:33]
	v_mfma_f32_16x16x32_bf16 v[26:29], v[146:149], v[198:201], v[26:29]
	v_mfma_f32_16x16x32_bf16 v[22:25], v[138:141], v[206:209], v[22:25]
	v_mfma_f32_16x16x32_bf16 v[18:21], v[146:149], v[206:209], v[18:21]
	v_mfma_f32_16x16x32_bf16 v[14:17], v[138:141], v[214:217], v[14:17]
	v_mfma_f32_16x16x32_bf16 v[10:13], v[146:149], v[214:217], v[10:13]
	v_mfma_f32_16x16x32_bf16 v[6:9], v[138:141], v[222:225], v[6:9]
	v_mfma_f32_16x16x32_bf16 v[2:5], v[146:149], v[222:225], v[2:5]
	v_mfma_f32_16x16x32_bf16 v[94:97], v[150:153], v[194:197], v[94:97]
	v_mfma_f32_16x16x32_bf16 v[90:93], v[186:189], v[194:197], v[90:93]
	v_mfma_f32_16x16x32_bf16 v[86:89], v[150:153], v[202:205], v[86:89]
	v_mfma_f32_16x16x32_bf16 v[82:85], v[186:189], v[202:205], v[82:85]
	v_mfma_f32_16x16x32_bf16 v[78:81], v[150:153], v[210:213], v[78:81]
	v_mfma_f32_16x16x32_bf16 v[74:77], v[186:189], v[210:213], v[74:77]
	v_mfma_f32_16x16x32_bf16 v[70:73], v[150:153], v[218:221], v[70:73]
	v_mfma_f32_16x16x32_bf16 v[66:69], v[186:189], v[218:221], v[66:69]
	v_mfma_f32_16x16x32_bf16 v[94:97], v[182:185], v[198:201], v[94:97]
	v_mfma_f32_16x16x32_bf16 v[90:93], v[190:193], v[198:201], v[90:93]
	v_mfma_f32_16x16x32_bf16 v[86:89], v[182:185], v[206:209], v[86:89]
	v_mfma_f32_16x16x32_bf16 v[82:85], v[190:193], v[206:209], v[82:85]
	v_mfma_f32_16x16x32_bf16 v[78:81], v[182:185], v[214:217], v[78:81]
	v_mfma_f32_16x16x32_bf16 v[74:77], v[190:193], v[214:217], v[74:77]
	v_mfma_f32_16x16x32_bf16 v[70:73], v[182:185], v[222:225], v[70:73]
	v_mfma_f32_16x16x32_bf16 v[66:69], v[190:193], v[222:225], v[66:69]
	s_barrier
.Lpeel_mid_st:
	s_add_i32 s76, 0, 0x18000
	s_add_i32 s77, 0, 0x1c000
	v_add_u32_e32 v146, s76, v169
	v_add_u32_e32 v190, s77, v169
	ds_read_b128 v[134:137], v146
	ds_read_b128 v[138:141], v146 offset:1024
	ds_read_b128 v[142:145], v146 offset:2048
	ds_read_b128 v[146:149], v146 offset:3072
	ds_read_b128 v[150:153], v190
	ds_read_b128 v[182:185], v190 offset:1024
	ds_read_b128 v[186:189], v190 offset:2048
	ds_read_b128 v[190:193], v190 offset:3072
	s_add_u32 s66, s66, 0x40000
	s_addc_u32 s67, s67, 0
	s_mov_b32 m0, s37
	v_lshl_add_u64 v[242:243], s[66:67], 0, v[154:155]
	ds_read_b128 v[194:197], v250 offset:32768
	ds_read_b128 v[198:201], v250 offset:33792
	ds_read_b128 v[202:205], v250 offset:34816
	ds_read_b128 v[206:209], v250 offset:35840
	ds_read_b128 v[210:213], v250 offset:36864
	ds_read_b128 v[214:217], v250 offset:37888
	ds_read_b128 v[218:221], v250 offset:38912
	ds_read_b128 v[222:225], v250 offset:39936
	global_load_lds_dwordx4 v[242:243], off
	v_lshl_add_u64 v[242:243], s[66:67], 0, v[158:159]
	s_mov_b32 m0, s68
	s_nop 0
	global_load_lds_dwordx4 v[242:243], off
	s_waitcnt vmcnt(8)
	s_waitcnt lgkmcnt(0)
	s_barrier
	s_waitcnt lgkmcnt(0)
	v_mfma_f32_16x16x32_bf16 v[62:65], v[134:137], v[194:197], v[62:65]
	v_mfma_f32_16x16x32_bf16 v[58:61], v[142:145], v[194:197], v[58:61]
	v_mfma_f32_16x16x32_bf16 v[54:57], v[134:137], v[202:205], v[54:57]
	v_mfma_f32_16x16x32_bf16 v[50:53], v[142:145], v[202:205], v[50:53]
	v_mfma_f32_16x16x32_bf16 v[46:49], v[134:137], v[210:213], v[46:49]
	v_mfma_f32_16x16x32_bf16 v[42:45], v[142:145], v[210:213], v[42:45]
	v_mfma_f32_16x16x32_bf16 v[38:41], v[134:137], v[218:221], v[38:41]
	v_mfma_f32_16x16x32_bf16 v[34:37], v[142:145], v[218:221], v[34:37]
	v_mfma_f32_16x16x32_bf16 v[62:65], v[138:141], v[198:201], v[62:65]
	v_mfma_f32_16x16x32_bf16 v[58:61], v[146:149], v[198:201], v[58:61]
	v_mfma_f32_16x16x32_bf16 v[54:57], v[138:141], v[206:209], v[54:57]
	v_mfma_f32_16x16x32_bf16 v[50:53], v[146:149], v[206:209], v[50:53]
	v_mfma_f32_16x16x32_bf16 v[46:49], v[138:141], v[214:217], v[46:49]
	v_mfma_f32_16x16x32_bf16 v[42:45], v[146:149], v[214:217], v[42:45]
	v_mfma_f32_16x16x32_bf16 v[38:41], v[138:141], v[222:225], v[38:41]
	v_mfma_f32_16x16x32_bf16 v[34:37], v[146:149], v[222:225], v[34:37]
	v_mfma_f32_16x16x32_bf16 v[126:129], v[150:153], v[194:197], v[126:129]
	v_mfma_f32_16x16x32_bf16 v[122:125], v[186:189], v[194:197], v[122:125]
	v_mfma_f32_16x16x32_bf16 v[118:121], v[150:153], v[202:205], v[118:121]
	v_mfma_f32_16x16x32_bf16 v[114:117], v[186:189], v[202:205], v[114:117]
	v_mfma_f32_16x16x32_bf16 v[110:113], v[150:153], v[210:213], v[110:113]
	v_mfma_f32_16x16x32_bf16 v[106:109], v[186:189], v[210:213], v[106:109]
	v_mfma_f32_16x16x32_bf16 v[102:105], v[150:153], v[218:221], v[102:105]
	v_mfma_f32_16x16x32_bf16 v[98:101], v[186:189], v[218:221], v[98:101]
	v_mfma_f32_16x16x32_bf16 v[126:129], v[182:185], v[198:201], v[126:129]
	v_mfma_f32_16x16x32_bf16 v[122:125], v[190:193], v[198:201], v[122:125]
	v_mfma_f32_16x16x32_bf16 v[118:121], v[182:185], v[206:209], v[118:121]
	v_mfma_f32_16x16x32_bf16 v[114:117], v[190:193], v[206:209], v[114:117]
	v_mfma_f32_16x16x32_bf16 v[110:113], v[182:185], v[214:217], v[110:113]
	v_mfma_f32_16x16x32_bf16 v[106:109], v[190:193], v[214:217], v[106:109]
	v_mfma_f32_16x16x32_bf16 v[102:105], v[182:185], v[222:225], v[102:105]
	v_mfma_f32_16x16x32_bf16 v[98:101], v[190:193], v[222:225], v[98:101]
	s_barrier
	s_add_i32 s66, s76, s16
	v_lshl_add_u64 v[226:227], v[226:227], 0, s[0:1]
	s_mov_b32 m0, s66
	ds_read_b128 v[194:197], v250 offset:49152
	ds_read_b128 v[198:201], v250 offset:50176
	ds_read_b128 v[202:205], v250 offset:51200
	ds_read_b128 v[206:209], v250 offset:52224
	ds_read_b128 v[210:213], v250 offset:53248
	ds_read_b128 v[214:217], v250 offset:54272
	ds_read_b128 v[218:221], v250 offset:55296
	ds_read_b128 v[222:225], v250 offset:56320
	global_load_lds_dwordx4 v[226:227], off
	s_add_i32 m0, s66, 0x2000
	s_add_u32 s64, s64, 0x40080
	v_lshl_add_u64 v[226:227], v[228:229], 0, s[0:1]
	s_addc_u32 s65, s65, 0
	s_add_i32 s66, s77, s16
	global_load_lds_dwordx4 v[226:227], off
	v_lshl_add_u64 v[226:227], s[64:65], 0, v[156:157]
	s_mov_b32 m0, s66
	s_nop 0
	global_load_lds_dwordx4 v[226:227], off
	v_lshl_add_u64 v[226:227], s[64:65], 0, v[160:161]
	s_add_i32 m0, s66, 0x2000
	s_nop 0
	global_load_lds_dwordx4 v[226:227], off
	v_lshl_add_u64 v[226:227], v[230:231], 0, s[0:1]
	s_mov_b32 m0, s71
	s_nop 0
	global_load_lds_dwordx4 v[226:227], off
	v_lshl_add_u64 v[226:227], v[232:233], 0, s[0:1]
	s_mov_b32 m0, s72
	s_nop 0
	global_load_lds_dwordx4 v[226:227], off
	s_waitcnt vmcnt(8)
	s_waitcnt lgkmcnt(0)
	s_barrier
	s_waitcnt lgkmcnt(0)
	v_mfma_f32_16x16x32_bf16 v[30:33], v[134:137], v[194:197], v[30:33]
	v_mfma_f32_16x16x32_bf16 v[26:29], v[142:145], v[194:197], v[26:29]
	v_mfma_f32_16x16x32_bf16 v[22:25], v[134:137], v[202:205], v[22:25]
	v_mfma_f32_16x16x32_bf16 v[18:21], v[142:145], v[202:205], v[18:21]
	v_mfma_f32_16x16x32_bf16 v[14:17], v[134:137], v[210:213], v[14:17]
	v_mfma_f32_16x16x32_bf16 v[10:13], v[142:145], v[210:213], v[10:13]
	v_mfma_f32_16x16x32_bf16 v[6:9], v[134:137], v[218:221], v[6:9]
	v_mfma_f32_16x16x32_bf16 v[2:5], v[142:145], v[218:221], v[2:5]
	v_mfma_f32_16x16x32_bf16 v[30:33], v[138:141], v[198:201], v[30:33]
	v_mfma_f32_16x16x32_bf16 v[26:29], v[146:149], v[198:201], v[26:29]
	v_mfma_f32_16x16x32_bf16 v[22:25], v[138:141], v[206:209], v[22:25]
	v_mfma_f32_16x16x32_bf16 v[18:21], v[146:149], v[206:209], v[18:21]
	v_mfma_f32_16x16x32_bf16 v[14:17], v[138:141], v[214:217], v[14:17]
	v_mfma_f32_16x16x32_bf16 v[10:13], v[146:149], v[214:217], v[10:13]
	v_mfma_f32_16x16x32_bf16 v[6:9], v[138:141], v[222:225], v[6:9]
	v_mfma_f32_16x16x32_bf16 v[2:5], v[146:149], v[222:225], v[2:5]
	v_mfma_f32_16x16x32_bf16 v[94:97], v[150:153], v[194:197], v[94:97]
	v_mfma_f32_16x16x32_bf16 v[90:93], v[186:189], v[194:197], v[90:93]
	v_mfma_f32_16x16x32_bf16 v[86:89], v[150:153], v[202:205], v[86:89]
	v_mfma_f32_16x16x32_bf16 v[82:85], v[186:189], v[202:205], v[82:85]
	v_mfma_f32_16x16x32_bf16 v[78:81], v[150:153], v[210:213], v[78:81]
	v_mfma_f32_16x16x32_bf16 v[74:77], v[186:189], v[210:213], v[74:77]
	v_mfma_f32_16x16x32_bf16 v[70:73], v[150:153], v[218:221], v[70:73]
	v_mfma_f32_16x16x32_bf16 v[66:69], v[186:189], v[218:221], v[66:69]
	v_mfma_f32_16x16x32_bf16 v[94:97], v[182:185], v[198:201], v[94:97]
	v_mfma_f32_16x16x32_bf16 v[90:93], v[190:193], v[198:201], v[90:93]
	v_mfma_f32_16x16x32_bf16 v[86:89], v[182:185], v[206:209], v[86:89]
	v_mfma_f32_16x16x32_bf16 v[82:85], v[190:193], v[206:209], v[82:85]
	v_mfma_f32_16x16x32_bf16 v[78:81], v[182:185], v[214:217], v[78:81]
	v_mfma_f32_16x16x32_bf16 v[74:77], v[190:193], v[214:217], v[74:77]
	v_mfma_f32_16x16x32_bf16 v[70:73], v[182:185], v[222:225], v[70:73]
	v_mfma_f32_16x16x32_bf16 v[66:69], v[190:193], v[222:225], v[66:69]
	s_barrier
	s_add_i32 s53, s53, 2
	s_add_u32 s62, s62, 0x100
	s_addc_u32 s63, s63, 0
	s_add_u32 s12, s12, 0x100
	s_addc_u32 s13, s13, 0
	s_cmp_gt_u32 s53, 13
	s_cbranch_scc1 .LBB0_875
